# v26 + P10 shift/scale loads of all 4 column blocks hoisted (as v19) with vmcnt recounted for LDS-staged stores; header waits no longer drain the flush stores
# speedup vs baseline: 1.0011x; 1.0011x over previous
; __device__ __forceinline__ float wave_sum(float v) { return lane63(wave_scan_incl(v)); }
; template <bool XSRC_BF, bool XDST_BF> ...
;     ...
;     for (int it = 0; it < niter; ++it) {
;         const int row = rown; if (row < 0) break;
;         const int b = seq_of_row(row);
;         float xv[4][8]; vu4 hraw[4];
; #pragma unroll
;         for (int j = 0; j < 4; ++j) { if (XSRC_BF) unpack8(nxb[j], xv[j]); else {
; #pragma unroll
;                 for (int e = 0; e < 8; ++e) xv[j][e] = nxf[j][e]; }
;             hraw[j] = nho[j]; }
;         rown = it + 1 < niter ? ROW_OF(it + 1) : -1;
;         if (rown >= 0) ROW_LOAD(rown)
;         if (ho) {
;             float hv[4][8]; float ss = 0.f;
; #pragma unroll
;             for (int j = 0; j < 4; ++j) { unpack8(hraw[j], hv[j]);
; #pragma unroll
;                 for (int e = 0; e < 8; ++e) ss += hv[j][e] * hv[j][e]; }
;             ss = wave_sum(ss);
;             const float r1 = rsqrtf(ss * (1.0f / DM) + EPSN);
; #pragma unroll
;             for (int j = 0; j < 4; ++j) { float gt[8]; load8f(mgate + (size_t)b * 12288 + 8 * lane + 512 * j, gt);
.LBB0_1093:
.LBB0_1094:
	s_mul_i32 s7, s11, s3
	s_sub_i32 s7, s9, s7
	s_xor_b32 s6, s10, s8
	s_add_i32 s8, s11, 1
	s_sub_i32 s9, s7, s3
	s_cmp_ge_u32 s7, s3
	s_cselect_b32 s8, s8, s11
	s_cselect_b32 s7, s9, s7
	s_add_i32 s9, s8, 1
	s_cmp_ge_u32 s7, s3
	s_cselect_b32 s3, s9, s8
	s_xor_b32 s3, s3, s6
	s_sub_i32 s31, s3, s6
	s_cmp_lt_i32 s31, 1
	s_cselect_b64 s[6:7], -1, 0
	s_xor_b64 s[4:5], s[4:5], -1
	s_or_b64 s[4:5], s[6:7], s[4:5]
	s_mov_b32 s30, 1
	s_and_b64 vcc, exec, s[4:5]
	s_cbranch_vccnz .LBB0_1101
	v_readlane_b32 s4, v254, 8
	v_mov_b32_e32 v67, 0
	v_readlane_b32 s5, v254, 9
	v_lshlrev_b32_e32 v4, 5, v1
	v_mov_b32_e32 v5, v67
	v_lshl_add_u64 v[68:69], s[4:5], 0, v[66:67]
	v_readlane_b32 s4, v254, 4
	v_readlane_b32 s5, v254, 5
	s_add_u32 s33, s82, 0x58000
	v_lshlrev_b32_e32 v2, 3, v1
	v_lshl_add_u64 v[70:71], s[4:5], 0, v[66:67]
	v_lshl_add_u64 v[4:5], s[82:83], 0, v[4:5]
	s_mov_b64 s[4:5], 0x1a000
	v_and_b32_e32 v66, 16, v66
	v_lshrrev_b32_e32 v1, 1, v1
	s_addc_u32 s34, s83, 0
	v_lshl_add_u64 v[72:73], v[4:5], 0, s[4:5]
	v_lshl_add_u64 v[74:75], s[84:85], 0, v[66:67]
	v_mul_u32_u24_e32 v1, 0x500, v1
	s_mov_b32 s3, 0
	s_mov_b64 s[4:5], 0x1000
	s_movk_i32 s35, 0x1000
	s_mov_b64 s[6:7], 0x1800
	v_mov_b32_e32 v84, 0x358637bd
	s_mov_b32 s36, 0x800000
	v_lshlrev_b32_e32 v66, 2, v2
	s_mov_b64 s[8:9], 0x2000
	s_movk_i32 s37, 0x600
	s_mov_b64 s[10:11], 0x3000
	s_movk_i32 s38, 0x3000
	s_mov_b64 s[12:13], 0x3800
	v_mov_b32_e32 v85, 0x8000
	v_mov_b32_e32 v86, 0xc000
	v_mov_b32_e32 v87, 0x3a000000
	s_waitcnt vmcnt(0)
	v_and_b32_e32 v234, 63, v0
	v_lshrrev_b32_e32 v235, 6, v0
	v_mul_u32_u24_e32 v246, 0x4800, v235
	v_lshrrev_b32_e32 v236, 1, v234
	v_and_b32_e32 v237, 1, v234
	v_lshlrev_b32_e32 v237, 4, v237
	v_mul_u32_u24_e32 v236, 0x90, v236
	v_add3_u32 v242, v246, v236, v237
	v_lshrrev_b32_e32 v236, 3, v234
	v_and_b32_e32 v237, 7, v234
	v_lshlrev_b32_e32 v237, 4, v237
	v_mul_u32_u24_e32 v248, 0x90, v236
	v_add3_u32 v243, v246, v248, v237
	v_mul_u32_u24_e32 v248, 0x1e0000, v236
	v_lshlrev_b32_e32 v235, 7, v235
	v_add3_u32 v248, v248, v237, v235
	v_mov_b32_e32 v249, 0
	v_lshl_add_u64 v[244:245], s[84:85], 0, v[248:249]
	s_mov_b32 s100, 0xf00000
	s_mov_b32 s101, 0
	s_branch .LBB0_1097
.LBB0_1096:
	v_sub_co_u32_e32 v76, vcc, s2, v85
	s_nop 0
	v_readfirstlane_b32 s17, v76
	s_lshr_b32 s17, s17, 12
	s_add_i32 s17, s17, 4
	s_lshr_b32 s39, s2, 13
	s_and_b64 s[26:27], vcc, exec
	s_cselect_b32 s17, s39, s17
	v_lshlrev_b32_e32 v124, 16, v34
	v_and_b32_e32 v125, 0xffff0000, v34
	v_lshlrev_b32_e32 v126, 16, v35
	v_and_b32_e32 v127, 0xffff0000, v35
	v_mad_u64_u32 v[34:35], s[26:27], s17, v86, v[72:73]
	v_lshlrev_b32_e32 v100, 16, v62
	v_and_b32_e32 v101, 0xffff0000, v62
	v_lshlrev_b32_e32 v102, 16, v63
	v_and_b32_e32 v103, 0xffff0000, v63
	v_lshlrev_b32_e32 v104, 16, v64
	v_and_b32_e32 v105, 0xffff0000, v64
	v_lshlrev_b32_e32 v106, 16, v65
	v_and_b32_e32 v107, 0xffff0000, v65
	v_lshlrev_b32_e32 v108, 16, v58
	v_and_b32_e32 v109, 0xffff0000, v58
	v_lshlrev_b32_e32 v110, 16, v59
	v_and_b32_e32 v111, 0xffff0000, v59
	v_lshlrev_b32_e32 v112, 16, v60
	v_and_b32_e32 v113, 0xffff0000, v60
	v_lshlrev_b32_e32 v114, 16, v61
	v_and_b32_e32 v115, 0xffff0000, v61
	v_lshlrev_b32_e32 v116, 16, v54
	v_and_b32_e32 v117, 0xffff0000, v54
	v_lshlrev_b32_e32 v118, 16, v55
	v_and_b32_e32 v119, 0xffff0000, v55
	v_lshlrev_b32_e32 v120, 16, v56
	v_and_b32_e32 v121, 0xffff0000, v56
	v_lshlrev_b32_e32 v122, 16, v57
	v_and_b32_e32 v123, 0xffff0000, v57
	global_load_dwordx4 v[54:57], v[34:35], off offset:16
	global_load_dwordx4 v[58:61], v[34:35], off
	global_load_dwordx4 v[62:65], v[34:35], off offset:2064
	global_load_dwordx4 v[76:79], v[34:35], off offset:2048
	v_add_co_u32_e32 v92, vcc, s35, v34
	v_lshl_add_u64 v[88:89], v[34:35], 0, s[4:5]
	s_nop 0
	v_addc_co_u32_e32 v93, vcc, 0, v35, vcc
	global_load_dwordx4 v[80:83], v[92:93], off
	s_nop 0
	global_load_dwordx4 v[88:91], v[88:89], off offset:16
	v_lshl_add_u64 v[34:35], v[34:35], 0, s[6:7]
	global_load_dwordx4 v[92:95], v[92:93], off offset:2048
	s_nop 0
	global_load_dwordx4 v[96:99], v[34:35], off offset:16
	v_lshlrev_b32_e32 v176, 16, v38
	v_and_b32_e32 v177, 0xffff0000, v38
	v_lshlrev_b32_e32 v172, 16, v39
	v_and_b32_e32 v173, 0xffff0000, v39
	v_pk_mul_f32 v[38:39], v[176:177], v[176:177]
	v_lshlrev_b32_e32 v128, 16, v36
	v_and_b32_e32 v129, 0xffff0000, v36
	v_pk_mul_f32 v[174:175], v[172:173], v[172:173]
	v_add_f32_e32 v36, v38, v39
	v_lshlrev_b32_e32 v170, 16, v40
	v_and_b32_e32 v171, 0xffff0000, v40
	v_add_f32_e32 v36, v174, v36
	v_lshlrev_b32_e32 v166, 16, v41
	v_and_b32_e32 v167, 0xffff0000, v41
	v_pk_mul_f32 v[40:41], v[170:171], v[170:171]
	v_add_f32_e32 v36, v175, v36
	v_add_f32_e32 v36, v40, v36
	v_pk_mul_f32 v[168:169], v[166:167], v[166:167]
	v_add_f32_e32 v36, v41, v36
	v_lshlrev_b32_e32 v164, 16, v42
	v_and_b32_e32 v165, 0xffff0000, v42
	v_add_f32_e32 v36, v168, v36
	v_lshlrev_b32_e32 v160, 16, v43
	v_and_b32_e32 v161, 0xffff0000, v43
	v_pk_mul_f32 v[42:43], v[164:165], v[164:165]
	v_add_f32_e32 v36, v169, v36
	v_add_f32_e32 v36, v42, v36
	v_pk_mul_f32 v[162:163], v[160:161], v[160:161]
	v_add_f32_e32 v36, v43, v36
	v_lshlrev_b32_e32 v158, 16, v44
	v_and_b32_e32 v159, 0xffff0000, v44
	v_add_f32_e32 v36, v162, v36
	v_lshlrev_b32_e32 v154, 16, v45
	v_and_b32_e32 v155, 0xffff0000, v45
	v_pk_mul_f32 v[44:45], v[158:159], v[158:159]
	v_add_f32_e32 v36, v163, v36
	v_add_f32_e32 v36, v44, v36
	v_pk_mul_f32 v[156:157], v[154:155], v[154:155]
	v_add_f32_e32 v36, v45, v36
	v_lshlrev_b32_e32 v152, 16, v46
	v_and_b32_e32 v153, 0xffff0000, v46
	v_add_f32_e32 v36, v156, v36
	v_lshlrev_b32_e32 v148, 16, v47
	v_and_b32_e32 v149, 0xffff0000, v47
; __device__ __forceinline__ vu4 pack8(const float (&f)[8]) { vu4 w; w.x = pg8::cvt_pk_bf16(f[0], f[1]); w.y = pg8::cvt_pk_bf16(f[2], f[3]); w.z = pg8::cvt_pk_bf16(f[4], f[5]); w.w = pg8::cvt_pk_bf16(f[6], f[7]); return w; }
; __device__ __forceinline__ float wave_sum(float v) { return lane63(wave_scan_incl(v)); }
; template <bool XSRC_BF, bool XDST_BF> ...
;     ...
;             ss = wave_sum(ss);
;             const float r1 = rsqrtf(ss * (1.0f / DM) + EPSN);
; #pragma unroll
;             for (int j = 0; j < 4; ++j) { float gt[8]; load8f(mgate + (size_t)b * 12288 + 8 * lane + 512 * j, gt);
; #pragma unroll
;                 for (int e = 0; e < 8; ++e) xv[j][e] += gt[e] * (hv[j][e] * r1); }
;         }
;         if (x_dst) {
; #pragma unroll
;             for (int j = 0; j < 4; ++j) { if (XDST_BF) *(vu4*)((bf16_t*)x_dst + (size_t)row * DM + 8 * lane + 512 * j) = pack8(xv[j]); else store8f(x_dst + (size_t)row * DM + 8 * lane + 512 * j, xv[j]); }
;         }
;         if (h || ug) {
;             float ss = 0.f;
; #pragma unroll
;             for (int j = 0; j < 4; ++j)
; #pragma unroll
;                 for (int e = 0; e < 8; ++e) ss += xv[j][e] * xv[j][e];
;             ss = wave_sum(ss);
;             const float r2 = rsqrtf(ss * (1.0f / DM) + EPSN);
; #pragma unroll
;             for (int j = 0; j < 4; ++j) { float sh[8], sc[8], o[8]; load8f(mpre + (size_t)b * 12288 + 8 * lane + 512 * j, sh); load8f(mpre + (size_t)b * 12288 + 2048 + 8 * lane + 512 * j, sc);
	v_pk_mul_f32 v[46:47], v[152:153], v[152:153]
	v_add_f32_e32 v36, v157, v36
	v_add_f32_e32 v36, v46, v36
	v_pk_mul_f32 v[150:151], v[148:149], v[148:149]
	v_add_f32_e32 v36, v47, v36
	v_lshlrev_b32_e32 v146, 16, v48
	v_and_b32_e32 v147, 0xffff0000, v48
	v_add_f32_e32 v36, v150, v36
	v_lshlrev_b32_e32 v142, 16, v49
	v_and_b32_e32 v143, 0xffff0000, v49
	v_pk_mul_f32 v[48:49], v[146:147], v[146:147]
	v_add_f32_e32 v36, v151, v36
	v_add_f32_e32 v36, v48, v36
	v_pk_mul_f32 v[144:145], v[142:143], v[142:143]
	v_add_f32_e32 v36, v49, v36
	v_lshlrev_b32_e32 v140, 16, v50
	v_and_b32_e32 v141, 0xffff0000, v50
	v_add_f32_e32 v36, v144, v36
	v_lshlrev_b32_e32 v136, 16, v51
	v_and_b32_e32 v137, 0xffff0000, v51
	v_pk_mul_f32 v[50:51], v[140:141], v[140:141]
	v_add_f32_e32 v36, v145, v36
	v_add_f32_e32 v36, v50, v36
	v_pk_mul_f32 v[138:139], v[136:137], v[136:137]
	v_add_f32_e32 v36, v51, v36
	v_lshlrev_b32_e32 v134, 16, v52
	v_and_b32_e32 v135, 0xffff0000, v52
	v_add_f32_e32 v36, v138, v36
	v_lshlrev_b32_e32 v132, 16, v53
	v_and_b32_e32 v133, 0xffff0000, v53
	v_pk_mul_f32 v[52:53], v[134:135], v[134:135]
	v_add_f32_e32 v36, v139, v36
	v_add_f32_e32 v36, v52, v36
	v_pk_mul_f32 v[34:35], v[132:133], v[132:133]
	v_add_f32_e32 v36, v53, v36
	v_add_f32_e32 v34, v34, v36
	v_add_f32_e32 v34, v35, v34
	v_mov_b32_e32 v35, 0
	v_lshlrev_b32_e32 v130, 16, v37
	v_add_f32_dpp v34, v34, v34 row_shr:1 row_mask:0xf bank_mask:0xf bound_ctrl:1
	v_and_b32_e32 v131, 0xffff0000, v37
	s_mul_hi_u32 s39, s17, 0xc000
	v_add_f32_dpp v34, v34, v34 row_shr:2 row_mask:0xf bank_mask:0xf bound_ctrl:1
	s_mul_i32 s17, s17, 0xc000
	s_nop 0
	v_add_f32_dpp v34, v34, v34 row_shr:4 row_mask:0xf bank_mask:0xf bound_ctrl:1
	s_nop 1
	v_add_f32_dpp v34, v34, v34 row_shr:8 row_mask:0xf bank_mask:0xf bound_ctrl:1
	s_nop 1
	v_mov_b32_dpp v35, v34 row_bcast:15 row_mask:0xa bank_mask:0xf
	v_add_f32_e32 v34, v34, v35
	v_mov_b32_e32 v35, 0
	s_nop 1
	v_mov_b32_dpp v35, v34 row_bcast:31 row_mask:0xc bank_mask:0xf
	v_add_f32_e32 v34, v34, v35
	s_nop 0
	v_readlane_b32 s26, v34, 63
	s_nop 1
	v_fma_f32 v34, s26, v87, v84
	v_mul_f32_e32 v35, 0x4b800000, v34
	v_cmp_gt_f32_e32 vcc, s36, v34
	s_lshl_b64 s[26:27], s[2:3], 12
	s_nop 0
	v_cndmask_b32_e32 v34, v34, v35, vcc
	v_rsq_f32_e32 v34, v34
	s_nop 0
	v_mul_f32_e32 v35, 0x45800000, v34
	v_cndmask_b32_e32 v50, v34, v35, vcc
	v_pk_mul_f32 v[34:35], v[50:51], v[176:177] op_sel_hi:[0,1]
	s_waitcnt vmcnt(6)
	v_pk_fma_f32 v[100:101], v[58:59], v[34:35], v[100:101]
	v_pk_mul_f32 v[34:35], v[50:51], v[172:173] op_sel_hi:[0,1]
	v_pk_fma_f32 v[102:103], v[60:61], v[34:35], v[102:103]
	v_pk_mul_f32 v[34:35], v[50:51], v[170:171] op_sel_hi:[0,1]
	v_pk_fma_f32 v[104:105], v[54:55], v[34:35], v[104:105]
	v_pk_mul_f32 v[34:35], v[50:51], v[166:167] op_sel_hi:[0,1]
	v_pk_fma_f32 v[106:107], v[56:57], v[34:35], v[106:107]
	v_pk_mul_f32 v[34:35], v[50:51], v[164:165] op_sel_hi:[0,1]
	s_waitcnt vmcnt(4)
	v_pk_fma_f32 v[44:45], v[76:77], v[34:35], v[108:109]
	v_pk_mul_f32 v[34:35], v[50:51], v[160:161] op_sel_hi:[0,1]
	v_pk_fma_f32 v[48:49], v[78:79], v[34:35], v[110:111]
	v_pk_mul_f32 v[34:35], v[50:51], v[158:159] op_sel_hi:[0,1]
	v_pk_fma_f32 v[42:43], v[62:63], v[34:35], v[112:113]
	v_pk_mul_f32 v[34:35], v[50:51], v[154:155] op_sel_hi:[0,1]
	v_pk_fma_f32 v[46:47], v[64:65], v[34:35], v[114:115]
	v_pk_mul_f32 v[34:35], v[50:51], v[152:153] op_sel_hi:[0,1]
	v_pk_mul_f32 v[52:53], v[50:51], v[140:141] op_sel_hi:[0,1]
	s_waitcnt vmcnt(3)
	v_pk_fma_f32 v[36:37], v[80:81], v[34:35], v[116:117]
	v_pk_mul_f32 v[34:35], v[50:51], v[148:149] op_sel_hi:[0,1]
	s_waitcnt vmcnt(1)
	v_pk_fma_f32 v[76:77], v[92:93], v[52:53], v[124:125]
	v_pk_mul_f32 v[52:53], v[50:51], v[136:137] op_sel_hi:[0,1]
	v_pk_fma_f32 v[40:41], v[82:83], v[34:35], v[118:119]
	v_pk_mul_f32 v[34:35], v[50:51], v[146:147] op_sel_hi:[0,1]
	v_pk_mul_f32 v[38:39], v[50:51], v[142:143] op_sel_hi:[0,1]
	v_pk_fma_f32 v[78:79], v[94:95], v[52:53], v[126:127]
	v_pk_mul_f32 v[52:53], v[50:51], v[134:135] op_sel_hi:[0,1]
	v_pk_mul_f32 v[50:51], v[50:51], v[132:133] op_sel_hi:[0,1]
	s_waitcnt vmcnt(0)
	v_pk_fma_f32 v[80:81], v[52:53], v[96:97], v[128:129]
	v_pk_fma_f32 v[82:83], v[50:51], v[98:99], v[130:131]
	v_lshl_add_u64 v[54:55], v[68:69], 0, s[26:27]
	v_cvt_pk_bf16_f32 v50, v100, v101
	v_cvt_pk_bf16_f32 v51, v102, v103
	v_cvt_pk_bf16_f32 v52, v104, v105
	v_cvt_pk_bf16_f32 v53, v106, v107
	v_pk_fma_f32 v[34:35], v[88:89], v[34:35], v[120:121]
	v_pk_fma_f32 v[38:39], v[90:91], v[38:39], v[122:123]
	global_store_dwordx4 v[54:55], v[50:53], off
	s_add_u32 s26, s33, s17
	s_addc_u32 s27, s34, s39
	v_cvt_pk_bf16_f32 v50, v44, v45
	v_cvt_pk_bf16_f32 v51, v48, v49
	v_cvt_pk_bf16_f32 v52, v42, v43
	v_cvt_pk_bf16_f32 v53, v46, v47
	global_store_dwordx4 v[54:55], v[50:53], off offset:1024
	v_lshl_add_u64 v[108:109], s[26:27], 0, v[66:67]
	v_add_co_u32_e32 v96, vcc, s38, v108
	v_cvt_pk_bf16_f32 v50, v36, v37
	v_cvt_pk_bf16_f32 v51, v40, v41
	v_cvt_pk_bf16_f32 v52, v34, v35
	v_cvt_pk_bf16_f32 v53, v38, v39
	global_store_dwordx4 v[54:55], v[50:53], off offset:2048
	v_addc_co_u32_e32 v97, vcc, 0, v109, vcc
	s_nop 0
	v_cvt_pk_bf16_f32 v50, v76, v77
	v_cvt_pk_bf16_f32 v51, v78, v79
	v_cvt_pk_bf16_f32 v52, v80, v81
	v_cvt_pk_bf16_f32 v53, v82, v83
	global_store_dwordx4 v[54:55], v[50:53], off offset:3072
	global_load_dwordx4 v[50:53], v66, s[26:27]
	s_nop 0
	global_load_dwordx4 v[54:57], v[96:97], off offset:-4096
	global_load_dwordx4 v[58:61], v66, s[26:27] offset:16
	v_lshl_add_u64 v[88:89], v[108:109], 0, s[8:9]
	global_load_dwordx4 v[62:65], v[88:89], off offset:16
	global_load_dwordx4 v[178:181], v[88:89], off offset:2048
; __device__ __forceinline__ vu4 pack8(const float (&f)[8]) { vu4 w; w.x = pg8::cvt_pk_bf16(f[0], f[1]); w.y = pg8::cvt_pk_bf16(f[2], f[3]); w.z = pg8::cvt_pk_bf16(f[4], f[5]); w.w = pg8::cvt_pk_bf16(f[6], f[7]); return w; }
; __device__ __forceinline__ float wave_sum(float v) { return lane63(wave_scan_incl(v)); }
; template <bool XSRC_BF, bool XDST_BF> ...
;     ...
;         if (h || ug) {
;             float ss = 0.f;
; #pragma unroll
;             for (int j = 0; j < 4; ++j)
; #pragma unroll
;                 for (int e = 0; e < 8; ++e) ss += xv[j][e] * xv[j][e];
;             ss = wave_sum(ss);
;             const float r2 = rsqrtf(ss * (1.0f / DM) + EPSN);
; #pragma unroll
;             for (int j = 0; j < 4; ++j) { float sh[8], sc[8], o[8]; load8f(mpre + (size_t)b * 12288 + 8 * lane + 512 * j, sh); load8f(mpre + (size_t)b * 12288 + 2048 + 8 * lane + 512 * j, sc);
; #pragma unroll
;                 for (int e = 0; e < 8; ++e) o[e] = xv[j][e] * r2 * sc[e] + sh[e];
;                 if (ug) { const int col = 8 * lane + 512 * j; *(vu4*)(ug + ((size_t)((col >> 4) * 1280 + (row >> 5))) * 768 + (row & 31) * 16 + (col & 8)) = pack8(o); }
;                 else *(vu4*)(h + (size_t)row * DM + 8 * lane + 512 * j) = pack8(o); }
	global_load_dwordx4 v[182:185], v66, s[26:27] offset:2048
	global_load_dwordx4 v[186:189], v66, s[26:27] offset:2064
	global_load_dwordx4 v[190:193], v[88:89], off offset:2064
	v_mov_b32_e32 v232, s35
	v_mov_b32_e32 v233, 0
	v_lshl_add_u64 v[234:235], v[108:109], 0, s[4:5]
	v_lshl_add_u64 v[230:231], v[108:109], 0, v[232:233]
	v_lshl_add_u64 v[236:237], v[108:109], 0, s[10:11]
	v_lshl_add_u64 v[238:239], v[108:109], 0, s[6:7]
	v_lshl_add_u64 v[240:241], v[108:109], 0, s[12:13]
	global_load_dwordx4 v[194:197], v[230:231], off
	global_load_dwordx4 v[198:201], v[96:97], off
	global_load_dwordx4 v[202:205], v[234:235], off offset:16
	global_load_dwordx4 v[210:213], v[236:237], off offset:16
	global_load_dwordx4 v[214:217], v[230:231], off offset:2048
	global_load_dwordx4 v[218:221], v[238:239], off offset:16
	global_load_dwordx4 v[222:225], v[96:97], off offset:2048
	global_load_dwordx4 v[226:229], v[240:241], off offset:16
	v_pk_mul_f32 v[90:91], v[100:101], v[100:101]
	v_pk_mul_f32 v[92:93], v[102:103], v[102:103]
	v_add_f32_e32 v90, v90, v91
	v_add_f32_e32 v90, v92, v90
	v_pk_mul_f32 v[94:95], v[104:105], v[104:105]
	v_add_f32_e32 v90, v93, v90
	v_add_f32_e32 v90, v94, v90
	v_pk_mul_f32 v[98:99], v[106:107], v[106:107]
	v_add_f32_e32 v90, v95, v90
	v_add_f32_e32 v90, v98, v90
	v_pk_mul_f32 v[110:111], v[44:45], v[44:45]
	v_add_f32_e32 v90, v99, v90
	v_add_f32_e32 v90, v110, v90
	v_pk_mul_f32 v[112:113], v[48:49], v[48:49]
	v_add_f32_e32 v90, v111, v90
	v_add_f32_e32 v90, v112, v90
	v_pk_mul_f32 v[114:115], v[42:43], v[42:43]
	v_add_f32_e32 v90, v113, v90
	v_add_f32_e32 v90, v114, v90
	v_pk_mul_f32 v[116:117], v[46:47], v[46:47]
	v_add_f32_e32 v90, v115, v90
	v_add_f32_e32 v90, v116, v90
	v_pk_mul_f32 v[118:119], v[36:37], v[36:37]
	v_add_f32_e32 v90, v117, v90
	v_add_f32_e32 v90, v118, v90
	v_pk_mul_f32 v[120:121], v[40:41], v[40:41]
	v_add_f32_e32 v90, v119, v90
	v_add_f32_e32 v90, v120, v90
	v_pk_mul_f32 v[122:123], v[34:35], v[34:35]
	v_add_f32_e32 v90, v121, v90
	v_add_f32_e32 v90, v122, v90
	v_pk_mul_f32 v[124:125], v[38:39], v[38:39]
	v_add_f32_e32 v90, v123, v90
	v_add_f32_e32 v90, v124, v90
	v_pk_mul_f32 v[126:127], v[76:77], v[76:77]
	v_add_f32_e32 v90, v125, v90
	v_add_f32_e32 v90, v126, v90
	v_pk_mul_f32 v[128:129], v[78:79], v[78:79]
	v_add_f32_e32 v90, v127, v90
	v_add_f32_e32 v90, v128, v90
	v_pk_mul_f32 v[130:131], v[80:81], v[80:81]
	v_add_f32_e32 v90, v129, v90
	v_add_f32_e32 v90, v130, v90
	v_pk_mul_f32 v[132:133], v[82:83], v[82:83]
	v_add_f32_e32 v90, v131, v90
	v_add_f32_e32 v90, v132, v90
	v_add_f32_e32 v90, v133, v90
	v_mov_b32_e32 v91, 0
	s_and_b64 s[14:15], s[14:15], s[24:25]
	v_add_f32_dpp v90, v90, v90 row_shr:1 row_mask:0xf bank_mask:0xf bound_ctrl:1
	s_add_i32 s30, s30, 1
	s_nop 0
	v_add_f32_dpp v90, v90, v90 row_shr:2 row_mask:0xf bank_mask:0xf bound_ctrl:1
	s_nop 1
	v_add_f32_dpp v90, v90, v90 row_shr:4 row_mask:0xf bank_mask:0xf bound_ctrl:1
	s_nop 1
	v_add_f32_dpp v90, v90, v90 row_shr:8 row_mask:0xf bank_mask:0xf bound_ctrl:1
	s_nop 1
	v_mov_b32_dpp v91, v90 row_bcast:15 row_mask:0xa bank_mask:0xf
	v_add_f32_e32 v90, v90, v91
	v_mov_b32_e32 v91, 0
	s_nop 1
	v_mov_b32_dpp v91, v90 row_bcast:31 row_mask:0xc bank_mask:0xf
	v_add_f32_e32 v90, v90, v91
	s_nop 0
	v_readlane_b32 s17, v90, 63
	s_nop 1
	v_fma_f32 v90, s17, v87, v84
	v_mul_f32_e32 v91, 0x4b800000, v90
	v_cmp_gt_f32_e32 vcc, s36, v90
	s_lshr_b32 s17, s2, 5
	s_lshl_b32 s2, s2, 5
	v_cndmask_b32_e32 v90, v90, v91, vcc
	v_rsq_f32_e32 v90, v90
	s_and_b32 s2, s2, 0x3e0
	s_and_b32 s98, s2, 0x60
	v_add_u32_e32 v246, s98, v242
	v_lshl_add_u64 v[112:113], v[74:75], 0, s[2:3]
	s_mov_b32 s2, s16
	v_mul_f32_e32 v91, 0x45800000, v90
	v_cndmask_b32_e32 v110, v90, v91, vcc
	v_pk_mul_f32 v[90:91], v[100:101], v[110:111] op_sel_hi:[1,0]
	v_pk_mul_f32 v[44:45], v[44:45], v[110:111] op_sel_hi:[1,0]
	s_waitcnt vmcnt(14)
	v_pk_fma_f32 v[50:51], v[54:55], v[90:91], v[50:51]
	v_pk_mul_f32 v[54:55], v[102:103], v[110:111] op_sel_hi:[1,0]
	v_cvt_pk_bf16_f32 v50, v50, v51
	v_pk_fma_f32 v[52:53], v[56:57], v[54:55], v[52:53]
	v_pk_mul_f32 v[54:55], v[104:105], v[110:111] op_sel_hi:[1,0]
	v_pk_mul_f32 v[56:57], v[106:107], v[110:111] op_sel_hi:[1,0]
	s_waitcnt vmcnt(12)
	v_pk_fma_f32 v[54:55], v[62:63], v[54:55], v[58:59]
	v_pk_fma_f32 v[56:57], v[64:65], v[56:57], v[60:61]
	v_add_u32_e32 v104, s17, v1
	v_cvt_pk_bf16_f32 v51, v52, v53
	v_cvt_pk_bf16_f32 v52, v54, v55
	v_cvt_pk_bf16_f32 v53, v56, v57
	v_mad_u64_u32 v[54:55], s[40:41], v104, s37, v[112:113]
	ds_write_b128 v246, v[50:53]
	s_nop 0
	v_pk_mul_f32 v[42:43], v[42:43], v[110:111] op_sel_hi:[1,0]
	v_pk_mul_f32 v[48:49], v[48:49], v[110:111] op_sel_hi:[1,0]
	v_pk_mul_f32 v[36:37], v[36:37], v[110:111] op_sel_hi:[1,0]
	v_pk_mul_f32 v[34:35], v[34:35], v[110:111] op_sel_hi:[1,0]
	v_pk_mul_f32 v[40:41], v[40:41], v[110:111] op_sel_hi:[1,0]
	s_waitcnt vmcnt(10)
	v_pk_fma_f32 v[44:45], v[44:45], v[178:179], v[182:183]
	v_pk_fma_f32 v[48:49], v[48:49], v[180:181], v[184:185]
	s_waitcnt vmcnt(8)
; __device__ __forceinline__ vu4 pack8(const float (&f)[8]) { vu4 w; w.x = pg8::cvt_pk_bf16(f[0], f[1]); w.y = pg8::cvt_pk_bf16(f[2], f[3]); w.z = pg8::cvt_pk_bf16(f[4], f[5]); w.w = pg8::cvt_pk_bf16(f[6], f[7]); return w; }
; template <bool XSRC_BF, bool XDST_BF> ...
;     ...
;             for (int j = 0; j < 4; ++j) { float sh[8], sc[8], o[8]; load8f(mpre + (size_t)b * 12288 + 8 * lane + 512 * j, sh); load8f(mpre + (size_t)b * 12288 + 2048 + 8 * lane + 512 * j, sc);
; #pragma unroll
;                 for (int e = 0; e < 8; ++e) o[e] = xv[j][e] * r2 * sc[e] + sh[e];
;                 if (ug) { const int col = 8 * lane + 512 * j; *(vu4*)(ug + ((size_t)((col >> 4) * 1280 + (row >> 5))) * 768 + (row & 31) * 16 + (col & 8)) = pack8(o); }
;                 else *(vu4*)(h + (size_t)row * DM + 8 * lane + 512 * j) = pack8(o); }
	v_pk_fma_f32 v[50:51], v[42:43], v[190:191], v[186:187]
	v_pk_mul_f32 v[42:43], v[46:47], v[110:111] op_sel_hi:[1,0]
	v_add_co_u32_e32 v58, vcc, s35, v108
	v_pk_fma_f32 v[46:47], v[42:43], v[192:193], v[188:189]
	v_cvt_pk_bf16_f32 v42, v44, v45
	v_cvt_pk_bf16_f32 v45, v46, v47
	v_add_u32_e32 v46, 0xa000, v104
	v_cvt_pk_bf16_f32 v43, v48, v49
	v_cvt_pk_bf16_f32 v44, v50, v51
	v_mad_u64_u32 v[46:47], s[26:27], v46, s37, v[112:113]
	ds_write_b128 v246, v[42:45] offset:4608
	v_addc_co_u32_e32 v59, vcc, 0, v109, vcc
	v_lshl_add_u64 v[50:51], v[108:109], 0, s[4:5]
	v_lshl_add_u64 v[54:55], v[108:109], 0, s[10:11]
	v_mov_b64_e32 v[64:65], v[4:5]
	v_mov_b64_e32 v[62:63], v[2:3]
	v_add_u32_e32 v2, 0x1e000, v104
	s_and_b64 vcc, exec, s[14:15]
	v_pk_mul_f32 v[4:5], v[78:79], v[110:111] op_sel_hi:[1,0]
	s_waitcnt vmcnt(6)
	v_pk_fma_f32 v[36:37], v[36:37], v[198:199], v[194:195]
	v_pk_fma_f32 v[40:41], v[40:41], v[200:201], v[196:197]
	v_mov_b64_e32 v[48:49], v[28:29]
	v_mov_b64_e32 v[46:47], v[26:27]
	s_waitcnt vmcnt(4)
	v_pk_fma_f32 v[42:43], v[34:35], v[210:211], v[202:203]
	v_pk_mul_f32 v[34:35], v[38:39], v[110:111] op_sel_hi:[1,0]
	s_nop 0
	v_pk_fma_f32 v[38:39], v[34:35], v[212:213], v[204:205]
	v_cvt_pk_bf16_f32 v34, v36, v37
	v_cvt_pk_bf16_f32 v37, v38, v39
	v_add_u32_e32 v38, 0x14000, v104
	v_cvt_pk_bf16_f32 v35, v40, v41
	v_cvt_pk_bf16_f32 v36, v42, v43
	v_mad_u64_u32 v[38:39], s[26:27], v38, s37, v[112:113]
	ds_write_b128 v246, v[34:37] offset:9216
	v_mov_b64_e32 v[40:41], v[12:13]
	v_mov_b64_e32 v[38:39], v[10:11]
	v_lshl_add_u64 v[34:35], v[108:109], 0, s[6:7]
	s_nop 0
	v_lshl_add_u64 v[34:35], v[108:109], 0, s[12:13]
	v_mov_b64_e32 v[60:61], v[8:9]
	v_mov_b64_e32 v[58:59], v[6:7]
	v_mad_u64_u32 v[6:7], s[14:15], v2, s37, v[112:113]
	v_pk_mul_f32 v[2:3], v[76:77], v[110:111] op_sel_hi:[1,0]
	v_pk_mul_f32 v[8:9], v[80:81], v[110:111] op_sel_hi:[1,0]
	v_pk_mul_f32 v[10:11], v[82:83], v[110:111] op_sel_hi:[1,0]
	v_mov_b64_e32 v[44:45], v[16:17]
	v_mov_b64_e32 v[52:53], v[32:33]
	v_mov_b64_e32 v[56:57], v[20:21]
	v_mov_b64_e32 v[36:37], v[24:25]
	v_mov_b64_e32 v[42:43], v[14:15]
	v_mov_b64_e32 v[50:51], v[30:31]
	v_mov_b64_e32 v[54:55], v[18:19]
	v_mov_b64_e32 v[34:35], v[22:23]
	s_waitcnt vmcnt(1)
	v_pk_fma_f32 v[2:3], v[2:3], v[222:223], v[214:215]
	v_pk_fma_f32 v[4:5], v[4:5], v[224:225], v[216:217]
	s_waitcnt vmcnt(0)
	v_pk_fma_f32 v[8:9], v[8:9], v[226:227], v[218:219]
	v_pk_fma_f32 v[10:11], v[10:11], v[228:229], v[220:221]
	v_cvt_pk_bf16_f32 v2, v2, v3
	v_cvt_pk_bf16_f32 v3, v4, v5
	v_cvt_pk_bf16_f32 v4, v8, v9
	v_cvt_pk_bf16_f32 v5, v10, v11
	ds_write_b128 v246, v[2:5] offset:13824
	s_cmp_lg_u32 s98, 0x60
	s_cbranch_scc1 .Lp10_noflush
	s_mul_i32 s98, s17, 0x600
	s_mov_b32 s99, 0
	v_lshl_add_u64 v[248:249], s[98:99], 0, v[244:245]
	s_waitcnt lgkmcnt(0)
	ds_read_b128 v[178:181], v243
	ds_read_b128 v[182:185], v243 offset:1152
	ds_read_b128 v[186:189], v243 offset:2304
	ds_read_b128 v[190:193], v243 offset:3456
	s_waitcnt lgkmcnt(3)
	global_store_dwordx4 v[248:249], v[178:181], off
	v_lshl_add_u64 v[248:249], s[100:101], 0, v[248:249]
	s_waitcnt lgkmcnt(2)
	global_store_dwordx4 v[248:249], v[182:185], off
	v_lshl_add_u64 v[248:249], s[100:101], 0, v[248:249]
	s_waitcnt lgkmcnt(1)
	global_store_dwordx4 v[248:249], v[186:189], off
	v_lshl_add_u64 v[248:249], s[100:101], 0, v[248:249]
	s_waitcnt lgkmcnt(0)
	global_store_dwordx4 v[248:249], v[190:193], off
	v_lshl_add_u64 v[248:249], s[100:101], 0, v[248:249]
	ds_read_b128 v[178:181], v243 offset:4608
	ds_read_b128 v[182:185], v243 offset:5760
	ds_read_b128 v[186:189], v243 offset:6912
	ds_read_b128 v[190:193], v243 offset:8064
	s_waitcnt lgkmcnt(3)
	global_store_dwordx4 v[248:249], v[178:181], off
	v_lshl_add_u64 v[248:249], s[100:101], 0, v[248:249]
	s_waitcnt lgkmcnt(2)
	global_store_dwordx4 v[248:249], v[182:185], off
	v_lshl_add_u64 v[248:249], s[100:101], 0, v[248:249]
	s_waitcnt lgkmcnt(1)
	global_store_dwordx4 v[248:249], v[186:189], off
	v_lshl_add_u64 v[248:249], s[100:101], 0, v[248:249]
	s_waitcnt lgkmcnt(0)
	global_store_dwordx4 v[248:249], v[190:193], off
	v_lshl_add_u64 v[248:249], s[100:101], 0, v[248:249]
	ds_read_b128 v[178:181], v243 offset:9216
	ds_read_b128 v[182:185], v243 offset:10368
	ds_read_b128 v[186:189], v243 offset:11520
	ds_read_b128 v[190:193], v243 offset:12672
	s_waitcnt lgkmcnt(3)
	global_store_dwordx4 v[248:249], v[178:181], off
	v_lshl_add_u64 v[248:249], s[100:101], 0, v[248:249]
	s_waitcnt lgkmcnt(2)
	global_store_dwordx4 v[248:249], v[182:185], off
	v_lshl_add_u64 v[248:249], s[100:101], 0, v[248:249]
	s_waitcnt lgkmcnt(1)
	global_store_dwordx4 v[248:249], v[186:189], off
	v_lshl_add_u64 v[248:249], s[100:101], 0, v[248:249]
	s_waitcnt lgkmcnt(0)
	global_store_dwordx4 v[248:249], v[190:193], off
	v_lshl_add_u64 v[248:249], s[100:101], 0, v[248:249]
	ds_read_b128 v[178:181], v243 offset:13824
	ds_read_b128 v[182:185], v243 offset:14976
	ds_read_b128 v[186:189], v243 offset:16128
	ds_read_b128 v[190:193], v243 offset:17280
	s_waitcnt lgkmcnt(3)
	global_store_dwordx4 v[248:249], v[178:181], off
	v_lshl_add_u64 v[248:249], s[100:101], 0, v[248:249]
	s_waitcnt lgkmcnt(2)
	global_store_dwordx4 v[248:249], v[182:185], off
	v_lshl_add_u64 v[248:249], s[100:101], 0, v[248:249]
	s_waitcnt lgkmcnt(1)
	global_store_dwordx4 v[248:249], v[186:189], off
	v_lshl_add_u64 v[248:249], s[100:101], 0, v[248:249]
	s_waitcnt lgkmcnt(0)
	global_store_dwordx4 v[248:249], v[190:193], off

; template <bool XSRC_BF, bool XDST_BF> ...
;     ...
;     int rown = ROW_OF(0);
;     if (rown >= 0) ROW_LOAD(rown)
;     for (int it = 0; it < niter; ++it) {
;         const int row = rown; if (row < 0) break;
;         const int b = seq_of_row(row);
;         float xv[4][8]; vu4 hraw[4];
; #pragma unroll
;         for (int j = 0; j < 4; ++j) { if (XSRC_BF) unpack8(nxb[j], xv[j]); else {
; #pragma unroll
;                 for (int e = 0; e < 8; ++e) xv[j][e] = nxf[j][e]; }
;             hraw[j] = nho[j]; }
;         rown = it + 1 < niter ? ROW_OF(it + 1) : -1;
;         if (rown >= 0) ROW_LOAD(rown)
.LBB0_1099:
	s_cmp_gt_i32 s16, -1
	s_waitcnt vmcnt(16)
	v_mov_b64_e32 v[10:11], v[38:39]
	s_waitcnt vmcnt(16)
	v_mov_b64_e32 v[14:15], v[42:43]
	s_waitcnt vmcnt(16)
	v_mov_b64_e32 v[26:27], v[46:47]
	s_waitcnt vmcnt(16)
	v_mov_b64_e32 v[30:31], v[50:51]
	v_mov_b64_e32 v[2:3], v[62:63]
	v_mov_b64_e32 v[6:7], v[58:59]
	v_mov_b64_e32 v[18:19], v[54:55]
	v_mov_b64_e32 v[22:23], v[34:35]
	s_cselect_b64 s[24:25], -1, 0
	s_cmp_lt_i32 s16, 0
	v_mov_b64_e32 v[12:13], v[40:41]
	v_mov_b64_e32 v[16:17], v[44:45]
	v_mov_b64_e32 v[28:29], v[48:49]
	v_mov_b64_e32 v[32:33], v[52:53]
	v_mov_b64_e32 v[4:5], v[64:65]
	v_mov_b64_e32 v[8:9], v[60:61]
	v_mov_b64_e32 v[20:21], v[56:57]
	v_mov_b64_e32 v[24:25], v[36:37]
	s_cbranch_scc1 .LBB0_1096
	s_mov_b32 s17, s3
	s_lshl_b64 s[26:27], s[16:17], 12
	v_lshl_add_u64 v[22:23], v[68:69], 0, s[26:27]
	v_lshl_add_u64 v[30:31], v[70:71], 0, s[26:27]
	global_load_dwordx4 v[2:5], v[22:23], off
	global_load_dwordx4 v[6:9], v[22:23], off offset:1024
	global_load_dwordx4 v[10:13], v[30:31], off
	global_load_dwordx4 v[14:17], v[30:31], off offset:1024
	global_load_dwordx4 v[18:21], v[22:23], off offset:2048
	s_nop 0
	global_load_dwordx4 v[22:25], v[22:23], off offset:3072
	s_nop 0
	global_load_dwordx4 v[26:29], v[30:31], off offset:2048
	s_nop 0
	global_load_dwordx4 v[30:33], v[30:31], off offset:3072
	s_branch .LBB0_1096
